# P4 Q/K epilogue: row-scale loads issued together, per-group vmcnt(0) waits removed, 8 wait states after every epilogue store before its data registers are rewritten
# baseline (speedup 1.0000x reference)
.LBB0_356:
.LBB0_357:
	s_lshl_b32 s23, s34, 8
	s_add_i32 s23, s23, s88
	v_or_b32_e32 v158, s23, v139
	s_lshl_b32 s3, s30, 8
	v_or_b32_e32 v156, 16, v158
	v_or_b32_e32 v154, 32, v158
	v_or_b32_e32 v152, 48, v158
	s_cmp_lt_i32 s30, 8
	s_mov_b64 s[0:1], -1
	v_ashrrev_i32_e32 v159, 31, v158
	v_ashrrev_i32_e32 v157, 31, v156
	v_ashrrev_i32_e32 v155, 31, v154
	v_ashrrev_i32_e32 v153, 31, v152
	s_cbranch_scc1 .LBB0_359
	v_lshl_add_u64 v[162:163], v[158:159], 2, s[12:13]
	global_load_dword v238, v[162:163], off
	global_load_dword v239, v[162:163], off offset:64
	global_load_dword v240, v[162:163], off offset:128
	global_load_dword v241, v[162:163], off offset:192
	global_load_dword v242, v[162:163], off offset:512
	global_load_dword v243, v[162:163], off offset:576
	global_load_dword v244, v[162:163], off offset:640
	global_load_dword v245, v[162:163], off offset:704
	s_nop 7
	s_add_i32 s0, s45, s3
	s_ashr_i32 s6, s23, 11
	s_ashr_i32 s7, s0, 6
	s_mul_i32 s6, s6, 20
	s_add_i32 s0, s6, s7
	s_ashr_i32 s1, s0, 31
	s_lshl_b64 s[0:1], s[0:1], 18
	s_add_u32 s0, s52, s0
	s_addc_u32 s1, s53, s1
	s_lshr_b32 s23, s23, 2
	s_and_b32 s23, s23, 0x1f0
	v_or_b32_e32 v136, s23, v192
	v_lshlrev_b32_e32 v136, 9, v136
	v_lshl_add_u64 v[168:169], s[0:1], 0, v[136:137]
	v_lshlrev_b32_e32 v160, 1, v138
	v_mov_b32_e32 v161, v137
	v_lshl_add_u64 v[170:171], v[168:169], 0, v[160:161]
	s_waitcnt vmcnt(0)
	v_fmamk_f32 v149, v238, 0x3a000000, v198
	v_cmp_gt_f32_e32 vcc, s60, v149
	v_mul_f32_e32 v164, 0x4b800000, v149
	s_nop 0
	v_cndmask_b32_e32 v149, v149, v164, vcc
	v_rsq_f32_e32 v149, v149
	s_nop 0
	v_mul_f32_e32 v164, 0x45800000, v149
	v_cndmask_b32_e32 v164, v149, v164, vcc
	v_pk_mul_f32 v[166:167], v[126:127], v[164:165] op_sel_hi:[1,0]
	v_pk_mul_f32 v[172:173], v[124:125], v[164:165] op_sel_hi:[1,0]
	v_pk_mul_f32 v[174:175], v[122:123], v[164:165] op_sel_hi:[1,0]
	v_pk_mul_f32 v[176:177], v[120:121], v[164:165] op_sel_hi:[1,0]
	v_cvt_pk_bf16_f32 v164, v172, v173
	v_cvt_pk_bf16_f32 v165, v166, v167
	v_lshlrev_b32_e32 v149, 4, v156
	v_cvt_pk_bf16_f32 v166, v176, v177
	v_cvt_pk_bf16_f32 v167, v174, v175
	global_store_dwordx4 v[170:171], v[164:167], off
	s_nop 7
	s_nop 1
	v_lshl_add_u64 v[166:167], v[156:157], 2, s[12:13]
	v_and_b32_e32 v164, 0x1f0, v149
	s_nop 7
	v_mov_b32_e32 v165, v137
	v_lshl_add_u64 v[168:169], v[168:169], 0, v[164:165]
	v_fmamk_f32 v149, v239, 0x3a000000, v198
	v_cmp_gt_f32_e32 vcc, s60, v149
	v_mul_f32_e32 v170, 0x4b800000, v149
	s_nop 0
	v_cndmask_b32_e32 v149, v149, v170, vcc
	v_rsq_f32_e32 v149, v149
	s_nop 0
	v_mul_f32_e32 v170, 0x45800000, v149
	v_cndmask_b32_e32 v170, v149, v170, vcc
	v_lshrrev_b32_e32 v149, 2, v154
	v_pk_mul_f32 v[172:173], v[110:111], v[170:171] op_sel_hi:[1,0]
	v_and_or_b32 v149, v149, s62, v193
	v_pk_mul_f32 v[174:175], v[108:109], v[170:171] op_sel_hi:[1,0]
	v_pk_mul_f32 v[176:177], v[106:107], v[170:171] op_sel_hi:[1,0]
	v_pk_mul_f32 v[178:179], v[104:105], v[170:171] op_sel_hi:[1,0]
	v_cvt_pk_bf16_f32 v170, v174, v175
	v_cvt_pk_bf16_f32 v171, v172, v173
	s_nop 0
	v_cvt_pk_bf16_f32 v172, v178, v179
	v_cvt_pk_bf16_f32 v173, v176, v177
	global_store_dwordx4 v[168:169], v[170:173], off
	s_nop 7
	v_lshlrev_b32_e32 v168, 9, v149
	v_mov_b32_e32 v169, v137
	v_lshl_add_u64 v[170:171], s[0:1], 0, v[168:169]
	v_lshl_add_u64 v[176:177], v[170:171], 0, v[160:161]
	v_lshl_add_u64 v[170:171], v[154:155], 2, s[12:13]
	s_nop 7
	v_fmamk_f32 v149, v240, 0x3a000000, v198
	v_cmp_gt_f32_e32 vcc, s60, v149
	v_mul_f32_e32 v172, 0x4b800000, v149
	s_nop 0
	v_cndmask_b32_e32 v149, v149, v172, vcc
	v_rsq_f32_e32 v149, v149
	s_nop 0
	v_mul_f32_e32 v172, 0x45800000, v149
	v_cndmask_b32_e32 v172, v149, v172, vcc
	v_lshrrev_b32_e32 v149, 2, v152
	v_pk_mul_f32 v[174:175], v[94:95], v[172:173] op_sel_hi:[1,0]
	v_pk_mul_f32 v[178:179], v[92:93], v[172:173] op_sel_hi:[1,0]
	v_pk_mul_f32 v[180:181], v[90:91], v[172:173] op_sel_hi:[1,0]
	v_pk_mul_f32 v[182:183], v[88:89], v[172:173] op_sel_hi:[1,0]
	v_cvt_pk_bf16_f32 v172, v178, v179
	v_cvt_pk_bf16_f32 v173, v174, v175
	v_and_or_b32 v149, v149, s62, v193
	v_cvt_pk_bf16_f32 v174, v182, v183
	v_cvt_pk_bf16_f32 v175, v180, v181
	global_store_dwordx4 v[176:177], v[172:175], off
	s_nop 7
	s_nop 1
	v_lshlrev_b32_e32 v172, 9, v149
	v_mov_b32_e32 v173, v137
	v_lshlrev_b32_e32 v149, 4, v152
	v_lshl_add_u64 v[176:177], s[0:1], 0, v[172:173]
	v_and_b32_e32 v174, 0x1f0, v149
	v_mov_b32_e32 v175, v137
	v_lshl_add_u64 v[178:179], v[176:177], 0, v[174:175]
	v_lshl_add_u64 v[176:177], v[152:153], 2, s[12:13]
	s_nop 7
	s_add_i32 s0, s50, s3
	v_fmamk_f32 v149, v241, 0x3a000000, v198
	v_cmp_gt_f32_e32 vcc, s60, v149
	v_mul_f32_e32 v180, 0x4b800000, v149
	s_nop 0
	v_cndmask_b32_e32 v149, v149, v180, vcc
	v_rsq_f32_e32 v149, v149
	s_nop 0
	v_mul_f32_e32 v180, 0x45800000, v149
	v_cndmask_b32_e32 v180, v149, v180, vcc
	v_pk_mul_f32 v[182:183], v[78:79], v[180:181] op_sel_hi:[1,0]
	v_pk_mul_f32 v[184:185], v[76:77], v[180:181] op_sel_hi:[1,0]
	v_pk_mul_f32 v[186:187], v[74:75], v[180:181] op_sel_hi:[1,0]
	v_pk_mul_f32 v[188:189], v[72:73], v[180:181] op_sel_hi:[1,0]
	v_cvt_pk_bf16_f32 v180, v184, v185
	v_cvt_pk_bf16_f32 v181, v182, v183
	s_nop 0
	v_cvt_pk_bf16_f32 v182, v188, v189
	v_cvt_pk_bf16_f32 v183, v186, v187
	global_store_dwordx4 v[178:179], v[180:183], off
	s_nop 7
	s_nop 1
	v_add_u32_e32 v180, 0x80, v158
	v_ashrrev_i32_e32 v149, 11, v180
	v_mad_i32_i24 v178, v149, 20, s7
	v_ashrrev_i32_e32 v179, 31, v178
	v_lshlrev_b64 v[178:179], 18, v[178:179]
	v_lshl_add_u64 v[188:189], s[52:53], 0, v[178:179]
	v_lshrrev_b32_e32 v178, 2, v180
	v_and_or_b32 v178, v178, s61, v192
	v_lshlrev_b32_e32 v178, 9, v178
	v_mov_b32_e32 v179, v137
	v_lshl_add_u64 v[180:181], v[188:189], 0, v[178:179]
	v_lshl_add_u64 v[184:185], v[180:181], 0, v[160:161]
	s_nop 7
	s_ashr_i32 s7, s0, 6
	s_add_i32 s0, s6, s7
	s_ashr_i32 s1, s0, 31
	s_lshl_b64 s[0:1], s[0:1], 18
	s_add_u32 s0, s52, s0
	s_addc_u32 s1, s53, s1
	v_fmamk_f32 v180, v242, 0x3a000000, v198
	v_cmp_gt_f32_e32 vcc, s60, v180
	v_mul_f32_e32 v181, 0x4b800000, v180
	s_nop 0
	v_cndmask_b32_e32 v180, v180, v181, vcc
	v_rsq_f32_e32 v180, v180
	s_nop 0
	v_mul_f32_e32 v181, 0x45800000, v180
	v_cndmask_b32_e32 v180, v180, v181, vcc
	v_pk_mul_f32 v[182:183], v[62:63], v[180:181] op_sel_hi:[1,0]
	v_pk_mul_f32 v[186:187], v[60:61], v[180:181] op_sel_hi:[1,0]
	v_pk_mul_f32 v[200:201], v[58:59], v[180:181] op_sel_hi:[1,0]
	v_pk_mul_f32 v[202:203], v[56:57], v[180:181] op_sel_hi:[1,0]
	v_cvt_pk_bf16_f32 v180, v186, v187
	v_cvt_pk_bf16_f32 v181, v182, v183
	s_nop 0
	v_cvt_pk_bf16_f32 v182, v202, v203
	v_cvt_pk_bf16_f32 v183, v200, v201
	global_store_dwordx4 v[184:185], v[180:183], off
	s_nop 7
	s_nop 1
	v_add_u32_e32 v182, 0x90, v158
	v_lshrrev_b32_e32 v180, 2, v182
	v_and_or_b32 v180, v180, s61, v192
	v_lshlrev_b32_e32 v180, 9, v180
	v_mov_b32_e32 v181, v137
	v_lshlrev_b32_e32 v182, 4, v182
	v_lshl_add_u64 v[184:185], v[188:189], 0, v[180:181]
	v_and_b32_e32 v182, 0x1f0, v182
	v_mov_b32_e32 v183, v137
	v_lshl_add_u64 v[200:201], v[184:185], 0, v[182:183]
	s_nop 7
	v_fmamk_f32 v184, v243, 0x3a000000, v198
	v_cmp_gt_f32_e32 vcc, s60, v184
	v_mul_f32_e32 v185, 0x4b800000, v184
	s_nop 0
	v_cndmask_b32_e32 v184, v184, v185, vcc
	v_rsq_f32_e32 v184, v184
	s_nop 0
	v_mul_f32_e32 v185, 0x45800000, v184
	v_cndmask_b32_e32 v184, v184, v185, vcc
	v_pk_mul_f32 v[186:187], v[46:47], v[184:185] op_sel_hi:[1,0]
	v_pk_mul_f32 v[202:203], v[44:45], v[184:185] op_sel_hi:[1,0]
	v_pk_mul_f32 v[204:205], v[42:43], v[184:185] op_sel_hi:[1,0]
	v_pk_mul_f32 v[206:207], v[40:41], v[184:185] op_sel_hi:[1,0]
	v_cvt_pk_bf16_f32 v184, v202, v203
	v_cvt_pk_bf16_f32 v185, v186, v187
	s_nop 0
	v_cvt_pk_bf16_f32 v186, v206, v207
	v_cvt_pk_bf16_f32 v187, v204, v205
	global_store_dwordx4 v[200:201], v[184:187], off
	s_nop 7
	s_nop 7
	v_fmamk_f32 v196, v244, 0x3a000000, v198
	v_cmp_gt_f32_e32 vcc, s60, v196
	v_mul_f32_e32 v199, 0x4b800000, v196
	v_add_u32_e32 v184, 0xa0, v158
	v_cndmask_b32_e32 v196, v196, v199, vcc
	v_rsq_f32_e32 v196, v196
	v_lshrrev_b32_e32 v184, 2, v184
	v_and_or_b32 v184, v184, s62, v192
	v_lshlrev_b32_e32 v184, 9, v184
	v_mov_b32_e32 v185, v137
	v_mul_f32_e32 v199, 0x45800000, v196
	v_lshl_add_u64 v[186:187], v[188:189], 0, v[184:185]
	v_cndmask_b32_e32 v200, v196, v199, vcc
	v_lshl_add_u64 v[186:187], v[186:187], 0, v[160:161]
	v_pk_mul_f32 v[202:203], v[30:31], v[200:201] op_sel_hi:[1,0]
	v_add_u32_e32 v196, 0xb0, v158
	v_pk_mul_f32 v[204:205], v[28:29], v[200:201] op_sel_hi:[1,0]
	v_pk_mul_f32 v[206:207], v[26:27], v[200:201] op_sel_hi:[1,0]
	v_pk_mul_f32 v[208:209], v[24:25], v[200:201] op_sel_hi:[1,0]
	v_cvt_pk_bf16_f32 v200, v204, v205
	v_cvt_pk_bf16_f32 v201, v202, v203
	s_nop 0
	v_cvt_pk_bf16_f32 v202, v208, v209
	v_cvt_pk_bf16_f32 v203, v206, v207
	global_store_dwordx4 v[186:187], v[200:203], off
	s_nop 7
	v_lshrrev_b32_e32 v186, 2, v196
	v_and_or_b32 v186, v186, s62, v192
	v_lshlrev_b32_e32 v186, 9, v186
	v_mov_b32_e32 v187, v137
	v_lshl_add_u64 v[200:201], v[188:189], 0, v[186:187]
	v_lshlrev_b32_e32 v188, 4, v196
	s_nop 7
	v_and_b32_e32 v188, 0x1f0, v188
	v_mov_b32_e32 v189, v137
	v_lshl_add_u64 v[204:205], v[200:201], 0, v[188:189]
	v_fmamk_f32 v196, v245, 0x3a000000, v198
	v_cmp_gt_f32_e32 vcc, s60, v196
	v_mul_f32_e32 v199, 0x4b800000, v196
	s_nop 0
	v_cndmask_b32_e32 v196, v196, v199, vcc
	v_rsq_f32_e32 v196, v196
	s_nop 0
	v_mul_f32_e32 v199, 0x45800000, v196
	v_cndmask_b32_e32 v200, v196, v199, vcc
	v_pk_mul_f32 v[202:203], v[14:15], v[200:201] op_sel_hi:[1,0]
	v_pk_mul_f32 v[206:207], v[12:13], v[200:201] op_sel_hi:[1,0]
	v_pk_mul_f32 v[208:209], v[10:11], v[200:201] op_sel_hi:[1,0]
	v_pk_mul_f32 v[210:211], v[8:9], v[200:201] op_sel_hi:[1,0]
	v_cvt_pk_bf16_f32 v200, v206, v207
	v_cvt_pk_bf16_f32 v201, v202, v203
	s_nop 0
	v_cvt_pk_bf16_f32 v202, v210, v211
	v_cvt_pk_bf16_f32 v203, v208, v209
	global_store_dwordx4 v[204:205], v[200:203], off
	s_nop 7
	v_lshl_add_u64 v[204:205], s[0:1], 0, v[136:137]
	s_nop 7
	v_lshl_add_u64 v[206:207], v[204:205], 0, v[160:161]
	v_fmamk_f32 v136, v238, 0x3a000000, v198
	v_cmp_gt_f32_e32 vcc, s60, v136
	v_mul_f32_e32 v196, 0x4b800000, v136
	s_nop 0
	v_cndmask_b32_e32 v136, v136, v196, vcc
	v_rsq_f32_e32 v136, v136
	s_nop 0
	v_mul_f32_e32 v196, 0x45800000, v136
	v_cndmask_b32_e32 v136, v136, v196, vcc
	v_pk_mul_f32 v[202:203], v[118:119], v[136:137] op_sel_hi:[1,0]
	v_pk_mul_f32 v[200:201], v[116:117], v[136:137] op_sel_hi:[1,0]
	v_pk_mul_f32 v[208:209], v[114:115], v[136:137] op_sel_hi:[1,0]
	v_pk_mul_f32 v[210:211], v[112:113], v[136:137] op_sel_hi:[1,0]
	v_cvt_pk_bf16_f32 v200, v200, v201
	v_cvt_pk_bf16_f32 v201, v202, v203
	s_nop 0
	v_cvt_pk_bf16_f32 v202, v210, v211
	v_cvt_pk_bf16_f32 v203, v208, v209
	global_store_dwordx4 v[206:207], v[200:203], off
	s_nop 7
	s_nop 7
	v_fmamk_f32 v136, v239, 0x3a000000, v198
	v_lshl_add_u64 v[200:201], v[204:205], 0, v[164:165]
	v_cmp_gt_f32_e32 vcc, s60, v136
	v_mul_f32_e32 v164, 0x4b800000, v136
	s_nop 0
	v_cndmask_b32_e32 v136, v136, v164, vcc
	v_rsq_f32_e32 v136, v136
	s_nop 0
	v_mul_f32_e32 v164, 0x45800000, v136
	v_cndmask_b32_e32 v136, v136, v164, vcc
	v_pk_mul_f32 v[166:167], v[102:103], v[136:137] op_sel_hi:[1,0]
	v_pk_mul_f32 v[164:165], v[100:101], v[136:137] op_sel_hi:[1,0]
	v_pk_mul_f32 v[202:203], v[98:99], v[136:137] op_sel_hi:[1,0]
	v_pk_mul_f32 v[204:205], v[96:97], v[136:137] op_sel_hi:[1,0]
	v_cvt_pk_bf16_f32 v164, v164, v165
	v_cvt_pk_bf16_f32 v165, v166, v167
	s_nop 0
	v_cvt_pk_bf16_f32 v166, v204, v205
	v_cvt_pk_bf16_f32 v167, v202, v203
	global_store_dwordx4 v[200:201], v[164:167], off
	s_nop 7
	s_nop 7
	v_fmamk_f32 v136, v240, 0x3a000000, v198
	v_lshl_add_u64 v[164:165], s[0:1], 0, v[168:169]
	v_lshl_add_u64 v[168:169], v[164:165], 0, v[160:161]
	v_cmp_gt_f32_e32 vcc, s60, v136
	v_mul_f32_e32 v164, 0x4b800000, v136
	s_nop 0
	v_cndmask_b32_e32 v136, v136, v164, vcc
	v_rsq_f32_e32 v136, v136
	s_nop 0
	v_mul_f32_e32 v164, 0x45800000, v136
	v_cndmask_b32_e32 v136, v136, v164, vcc
	v_pk_mul_f32 v[166:167], v[86:87], v[136:137] op_sel_hi:[1,0]
	v_pk_mul_f32 v[164:165], v[84:85], v[136:137] op_sel_hi:[1,0]
	v_pk_mul_f32 v[170:171], v[82:83], v[136:137] op_sel_hi:[1,0]
	v_pk_mul_f32 v[200:201], v[80:81], v[136:137] op_sel_hi:[1,0]
	v_cvt_pk_bf16_f32 v164, v164, v165
	v_cvt_pk_bf16_f32 v165, v166, v167
	s_nop 0
	v_cvt_pk_bf16_f32 v166, v200, v201
	v_cvt_pk_bf16_f32 v167, v170, v171
	global_store_dwordx4 v[168:169], v[164:167], off
	s_nop 7
	s_nop 7
	v_fmamk_f32 v136, v241, 0x3a000000, v198
	v_lshl_add_u64 v[164:165], s[0:1], 0, v[172:173]
	v_lshl_add_u64 v[168:169], v[164:165], 0, v[174:175]
	v_cmp_gt_f32_e32 vcc, s60, v136
	v_mul_f32_e32 v164, 0x4b800000, v136
	s_mov_b64 s[0:1], 0
	v_cndmask_b32_e32 v136, v136, v164, vcc
	v_rsq_f32_e32 v136, v136
	s_nop 0
	v_mul_f32_e32 v164, 0x45800000, v136
	v_cndmask_b32_e32 v136, v136, v164, vcc
	v_pk_mul_f32 v[166:167], v[70:71], v[136:137] op_sel_hi:[1,0]
	v_pk_mul_f32 v[164:165], v[68:69], v[136:137] op_sel_hi:[1,0]
	v_pk_mul_f32 v[170:171], v[66:67], v[136:137] op_sel_hi:[1,0]
	v_pk_mul_f32 v[172:173], v[64:65], v[136:137] op_sel_hi:[1,0]
	v_cvt_pk_bf16_f32 v164, v164, v165
	v_cvt_pk_bf16_f32 v165, v166, v167
	s_nop 0
	v_cvt_pk_bf16_f32 v166, v172, v173
	v_cvt_pk_bf16_f32 v167, v170, v171
	global_store_dwordx4 v[168:169], v[164:167], off
	s_nop 7
	s_nop 7
	v_fmamk_f32 v136, v242, 0x3a000000, v198
	v_mad_i32_i24 v164, v149, 20, s7
	v_cmp_gt_f32_e32 vcc, s60, v136
	v_mul_f32_e32 v149, 0x4b800000, v136
	v_ashrrev_i32_e32 v165, 31, v164
	v_cndmask_b32_e32 v136, v136, v149, vcc
	v_rsq_f32_e32 v136, v136
	v_lshlrev_b64 v[164:165], 18, v[164:165]
	v_lshl_add_u64 v[168:169], s[52:53], 0, v[164:165]
	v_lshl_add_u64 v[164:165], v[168:169], 0, v[178:179]
	v_mul_f32_e32 v149, 0x45800000, v136
	v_cndmask_b32_e32 v136, v136, v149, vcc
	v_lshl_add_u64 v[170:171], v[164:165], 0, v[160:161]
	v_pk_mul_f32 v[166:167], v[54:55], v[136:137] op_sel_hi:[1,0]
	v_pk_mul_f32 v[164:165], v[52:53], v[136:137] op_sel_hi:[1,0]
	v_pk_mul_f32 v[172:173], v[50:51], v[136:137] op_sel_hi:[1,0]
	v_pk_mul_f32 v[174:175], v[48:49], v[136:137] op_sel_hi:[1,0]
	v_cvt_pk_bf16_f32 v164, v164, v165
	v_cvt_pk_bf16_f32 v165, v166, v167
	s_nop 0
	v_cvt_pk_bf16_f32 v166, v174, v175
	v_cvt_pk_bf16_f32 v167, v172, v173
	global_store_dwordx4 v[170:171], v[164:167], off
	s_nop 7
	s_nop 7
	v_fmamk_f32 v136, v243, 0x3a000000, v198
	v_cmp_gt_f32_e32 vcc, s60, v136
	v_mul_f32_e32 v149, 0x4b800000, v136
	v_lshl_add_u64 v[164:165], v[168:169], 0, v[180:181]
	v_cndmask_b32_e32 v136, v136, v149, vcc
	v_rsq_f32_e32 v136, v136
	v_lshl_add_u64 v[170:171], v[164:165], 0, v[182:183]
	v_mul_f32_e32 v149, 0x45800000, v136
	v_cndmask_b32_e32 v136, v136, v149, vcc
	v_pk_mul_f32 v[166:167], v[38:39], v[136:137] op_sel_hi:[1,0]
	v_pk_mul_f32 v[164:165], v[36:37], v[136:137] op_sel_hi:[1,0]
	v_pk_mul_f32 v[172:173], v[34:35], v[136:137] op_sel_hi:[1,0]
	v_pk_mul_f32 v[174:175], v[32:33], v[136:137] op_sel_hi:[1,0]
	v_cvt_pk_bf16_f32 v164, v164, v165
	v_cvt_pk_bf16_f32 v165, v166, v167
	s_nop 0
	v_cvt_pk_bf16_f32 v166, v174, v175
	v_cvt_pk_bf16_f32 v167, v172, v173
	global_store_dwordx4 v[170:171], v[164:167], off
	s_nop 7
	s_nop 7
	v_fmamk_f32 v136, v244, 0x3a000000, v198
	v_cmp_gt_f32_e32 vcc, s60, v136
	v_mul_f32_e32 v149, 0x4b800000, v136
	v_lshl_add_u64 v[164:165], v[168:169], 0, v[184:185]
	v_cndmask_b32_e32 v136, v136, v149, vcc
	v_rsq_f32_e32 v136, v136
	v_lshl_add_u64 v[160:161], v[164:165], 0, v[160:161]
	v_mul_f32_e32 v149, 0x45800000, v136
	v_cndmask_b32_e32 v136, v136, v149, vcc
	v_pk_mul_f32 v[166:167], v[22:23], v[136:137] op_sel_hi:[1,0]
	v_pk_mul_f32 v[164:165], v[20:21], v[136:137] op_sel_hi:[1,0]
	v_pk_mul_f32 v[170:171], v[18:19], v[136:137] op_sel_hi:[1,0]
	v_pk_mul_f32 v[172:173], v[16:17], v[136:137] op_sel_hi:[1,0]
	v_cvt_pk_bf16_f32 v164, v164, v165
	v_cvt_pk_bf16_f32 v165, v166, v167
	s_nop 0
	v_cvt_pk_bf16_f32 v166, v172, v173
	v_cvt_pk_bf16_f32 v167, v170, v171
	global_store_dwordx4 v[160:161], v[164:167], off
	s_nop 7
	s_nop 7
	v_lshl_add_u64 v[160:161], v[168:169], 0, v[186:187]
	v_lshl_add_u64 v[164:165], v[160:161], 0, v[188:189]
	v_fmamk_f32 v136, v245, 0x3a000000, v198
	v_cmp_gt_f32_e32 vcc, s60, v136
	v_mul_f32_e32 v149, 0x4b800000, v136
	s_nop 0
	v_cndmask_b32_e32 v136, v136, v149, vcc
	v_rsq_f32_e32 v136, v136
	s_nop 0
	v_mul_f32_e32 v149, 0x45800000, v136
	v_cndmask_b32_e32 v136, v136, v149, vcc
	v_pk_mul_f32 v[162:163], v[6:7], v[136:137] op_sel_hi:[1,0]
	v_pk_mul_f32 v[160:161], v[4:5], v[136:137] op_sel_hi:[1,0]
	v_pk_mul_f32 v[166:167], v[2:3], v[136:137] op_sel_hi:[1,0]
	v_pk_mul_f32 v[168:169], v[0:1], v[136:137] op_sel_hi:[1,0]
	v_cvt_pk_bf16_f32 v160, v160, v161
	v_cvt_pk_bf16_f32 v161, v162, v163
	s_nop 0
	v_cvt_pk_bf16_f32 v162, v168, v169
	v_cvt_pk_bf16_f32 v163, v166, v167
	global_store_dwordx4 v[164:165], v[160:163], off
	s_nop 7
.LBB0_359:
	s_andn2_b64 vcc, exec, s[0:1]
	s_cbranch_vccnz .LBB0_361
	v_lshl_add_u64 v[160:161], v[158:159], 2, s[12:13]
	global_load_dword v238, v[160:161], off
	global_load_dword v239, v[160:161], off offset:64
	global_load_dword v240, v[160:161], off offset:128
	global_load_dword v241, v[160:161], off offset:192
	global_load_dword v242, v[160:161], off offset:512
	global_load_dword v243, v[160:161], off offset:576
	global_load_dword v244, v[160:161], off offset:640
	global_load_dword v245, v[160:161], off offset:704
	s_nop 7
	v_or_b32_e32 v162, s3, v191
	v_lshlrev_b64 v[158:159], 12, v[158:159]
	v_ashrrev_i32_e32 v163, 31, v162
	v_lshl_add_u64 v[158:159], s[48:49], 0, v[158:159]
	v_lshlrev_b64 v[162:163], 1, v[162:163]
	v_lshl_add_u64 v[158:159], v[158:159], 0, v[162:163]
	v_lshl_add_u64 v[164:165], v[156:157], 2, s[12:13]
	s_mov_b32 s3, 0x80000
	s_mov_b64 s[0:1], 0x80000
	s_waitcnt vmcnt(0)
	v_fmamk_f32 v136, v238, 0x3a000000, v198
	v_mul_f32_e32 v149, 0x4b800000, v136
	v_cmp_gt_f32_e32 vcc, s60, v136
	s_nop 1
	v_cndmask_b32_e32 v136, v136, v149, vcc
	v_rsq_f32_e32 v136, v136
	s_nop 0
	v_mul_f32_e32 v149, 0x45800000, v136
	v_cndmask_b32_e32 v136, v136, v149, vcc
	v_mul_f32_e32 v136, 0x3e38aa3b, v136
	v_pk_mul_f32 v[126:127], v[126:127], v[136:137] op_sel_hi:[1,0]
	v_pk_mul_f32 v[124:125], v[124:125], v[136:137] op_sel_hi:[1,0]
	v_pk_mul_f32 v[122:123], v[122:123], v[136:137] op_sel_hi:[1,0]
	v_pk_mul_f32 v[120:121], v[120:121], v[136:137] op_sel_hi:[1,0]
	v_pk_mul_f32 v[166:167], v[114:115], v[136:137] op_sel_hi:[1,0]
	v_pk_mul_f32 v[168:169], v[112:113], v[136:137] op_sel_hi:[1,0]
	v_cvt_pk_bf16_f32 v112, v124, v125
	v_cvt_pk_bf16_f32 v113, v126, v127
	v_cvt_pk_bf16_f32 v114, v120, v121
	v_cvt_pk_bf16_f32 v115, v122, v123
	v_pk_mul_f32 v[118:119], v[118:119], v[136:137] op_sel_hi:[1,0]
	v_pk_mul_f32 v[116:117], v[116:117], v[136:137] op_sel_hi:[1,0]
	global_store_dwordx4 v[158:159], v[112:115], off
	s_nop 7
	s_nop 1
	v_cvt_pk_bf16_f32 v112, v116, v117
	v_cvt_pk_bf16_f32 v113, v118, v119
	v_cvt_pk_bf16_f32 v114, v168, v169
	v_cvt_pk_bf16_f32 v115, v166, v167
	global_store_dwordx4 v[158:159], v[112:115], off offset:256
	s_nop 7
	s_nop 7
	s_nop 0
	v_lshlrev_b64 v[112:113], 12, v[156:157]
	v_lshl_add_u64 v[112:113], s[48:49], 0, v[112:113]
	v_lshl_add_u64 v[112:113], v[112:113], 0, v[162:163]
	v_fmamk_f32 v114, v239, 0x3a000000, v198
	v_mul_f32_e32 v115, 0x4b800000, v114
	v_cmp_gt_f32_e32 vcc, s60, v114
	s_nop 1
	v_cndmask_b32_e32 v114, v114, v115, vcc
	v_rsq_f32_e32 v116, v114
	v_lshl_add_u64 v[114:115], v[154:155], 2, s[12:13]
	v_mul_f32_e32 v117, 0x45800000, v116
	v_cndmask_b32_e32 v116, v116, v117, vcc
	v_mul_f32_e32 v116, 0x3e38aa3b, v116
	v_pk_mul_f32 v[110:111], v[110:111], v[116:117] op_sel_hi:[1,0]
	v_pk_mul_f32 v[108:109], v[108:109], v[116:117] op_sel_hi:[1,0]
	v_pk_mul_f32 v[106:107], v[106:107], v[116:117] op_sel_hi:[1,0]
	v_pk_mul_f32 v[104:105], v[104:105], v[116:117] op_sel_hi:[1,0]
	v_pk_mul_f32 v[102:103], v[102:103], v[116:117] op_sel_hi:[1,0]
	v_pk_mul_f32 v[100:101], v[100:101], v[116:117] op_sel_hi:[1,0]
	v_pk_mul_f32 v[118:119], v[98:99], v[116:117] op_sel_hi:[1,0]
	v_pk_mul_f32 v[116:117], v[96:97], v[116:117] op_sel_hi:[1,0]
	v_cvt_pk_bf16_f32 v96, v108, v109
	v_cvt_pk_bf16_f32 v97, v110, v111
	v_cvt_pk_bf16_f32 v98, v104, v105
	v_cvt_pk_bf16_f32 v99, v106, v107
	global_store_dwordx4 v[112:113], v[96:99], off
	s_nop 7
	s_nop 1
	v_cvt_pk_bf16_f32 v96, v100, v101
	v_cvt_pk_bf16_f32 v97, v102, v103
	v_cvt_pk_bf16_f32 v98, v116, v117
	v_cvt_pk_bf16_f32 v99, v118, v119
	global_store_dwordx4 v[112:113], v[96:99], off offset:256
	s_nop 7
	s_nop 7
	s_nop 0
	v_lshlrev_b64 v[96:97], 12, v[154:155]
	v_lshl_add_u64 v[96:97], s[48:49], 0, v[96:97]
	v_lshl_add_u64 v[96:97], v[96:97], 0, v[162:163]
	v_fmamk_f32 v98, v240, 0x3a000000, v198
	v_mul_f32_e32 v99, 0x4b800000, v98
	v_cmp_gt_f32_e32 vcc, s60, v98
	s_nop 1
	v_cndmask_b32_e32 v98, v98, v99, vcc
	v_rsq_f32_e32 v100, v98
	v_lshl_add_u64 v[98:99], v[152:153], 2, s[12:13]
	v_mul_f32_e32 v101, 0x45800000, v100
	v_cndmask_b32_e32 v100, v100, v101, vcc
	v_mul_f32_e32 v100, 0x3e38aa3b, v100
	v_pk_mul_f32 v[94:95], v[94:95], v[100:101] op_sel_hi:[1,0]
	v_pk_mul_f32 v[92:93], v[92:93], v[100:101] op_sel_hi:[1,0]
	v_pk_mul_f32 v[90:91], v[90:91], v[100:101] op_sel_hi:[1,0]
	v_pk_mul_f32 v[88:89], v[88:89], v[100:101] op_sel_hi:[1,0]
	v_pk_mul_f32 v[86:87], v[86:87], v[100:101] op_sel_hi:[1,0]
	v_pk_mul_f32 v[84:85], v[84:85], v[100:101] op_sel_hi:[1,0]
	v_pk_mul_f32 v[102:103], v[82:83], v[100:101] op_sel_hi:[1,0]
	v_pk_mul_f32 v[100:101], v[80:81], v[100:101] op_sel_hi:[1,0]
	v_cvt_pk_bf16_f32 v80, v92, v93
	v_cvt_pk_bf16_f32 v81, v94, v95
	v_cvt_pk_bf16_f32 v82, v88, v89
	v_cvt_pk_bf16_f32 v83, v90, v91
	global_store_dwordx4 v[96:97], v[80:83], off
	s_nop 7
	s_nop 1
	v_cvt_pk_bf16_f32 v80, v84, v85
	v_cvt_pk_bf16_f32 v81, v86, v87
	v_cvt_pk_bf16_f32 v82, v100, v101
	v_cvt_pk_bf16_f32 v83, v102, v103
	global_store_dwordx4 v[96:97], v[80:83], off offset:256
	s_nop 7
	s_nop 7
	v_fmamk_f32 v80, v241, 0x3a000000, v198
	v_mul_f32_e32 v81, 0x4b800000, v80
	v_cmp_gt_f32_e32 vcc, s60, v80
	s_nop 1
	v_cndmask_b32_e32 v80, v80, v81, vcc
	v_rsq_f32_e32 v82, v80
	v_lshlrev_b64 v[80:81], 12, v[152:153]
	v_lshl_add_u64 v[80:81], s[48:49], 0, v[80:81]
	v_lshl_add_u64 v[80:81], v[80:81], 0, v[162:163]
	v_mul_f32_e32 v83, 0x45800000, v82
	v_cndmask_b32_e32 v82, v82, v83, vcc
	v_mul_f32_e32 v82, 0x3e38aa3b, v82
	v_pk_mul_f32 v[78:79], v[78:79], v[82:83] op_sel_hi:[1,0]
	v_pk_mul_f32 v[76:77], v[76:77], v[82:83] op_sel_hi:[1,0]
	v_pk_mul_f32 v[74:75], v[74:75], v[82:83] op_sel_hi:[1,0]
	v_pk_mul_f32 v[72:73], v[72:73], v[82:83] op_sel_hi:[1,0]
	v_pk_mul_f32 v[70:71], v[70:71], v[82:83] op_sel_hi:[1,0]
	v_pk_mul_f32 v[68:69], v[68:69], v[82:83] op_sel_hi:[1,0]
	v_pk_mul_f32 v[84:85], v[66:67], v[82:83] op_sel_hi:[1,0]
	v_pk_mul_f32 v[82:83], v[64:65], v[82:83] op_sel_hi:[1,0]
	v_cvt_pk_bf16_f32 v64, v76, v77
	v_cvt_pk_bf16_f32 v65, v78, v79
	v_cvt_pk_bf16_f32 v66, v72, v73
	v_cvt_pk_bf16_f32 v67, v74, v75
	global_store_dwordx4 v[80:81], v[64:67], off
	s_nop 7
	s_nop 1
	v_cvt_pk_bf16_f32 v64, v68, v69
	v_cvt_pk_bf16_f32 v65, v70, v71
	v_cvt_pk_bf16_f32 v66, v82, v83
	v_cvt_pk_bf16_f32 v67, v84, v85
	global_store_dwordx4 v[80:81], v[64:67], off offset:256
	s_nop 7
	s_nop 7
	s_nop 0
	v_lshl_add_u64 v[64:65], v[158:159], 0, s[0:1]
	s_mov_b64 s[0:1], 0x90000
	v_fmamk_f32 v66, v242, 0x3a000000, v198
	v_mul_f32_e32 v67, 0x4b800000, v66
	v_cmp_gt_f32_e32 vcc, s60, v66
	s_nop 1
	v_cndmask_b32_e32 v66, v66, v67, vcc
	v_rsq_f32_e32 v68, v66
	v_add_co_u32_e64 v66, s[6:7], s3, v158
	s_mov_b32 s3, 0x90000
	v_mul_f32_e32 v69, 0x45800000, v68
	v_cndmask_b32_e32 v68, v68, v69, vcc
	v_mul_f32_e32 v68, 0x3e38aa3b, v68
	v_addc_co_u32_e64 v67, s[6:7], 0, v159, s[6:7]
	v_pk_mul_f32 v[62:63], v[62:63], v[68:69] op_sel_hi:[1,0]
	v_pk_mul_f32 v[60:61], v[60:61], v[68:69] op_sel_hi:[1,0]
	v_pk_mul_f32 v[58:59], v[58:59], v[68:69] op_sel_hi:[1,0]
	v_pk_mul_f32 v[56:57], v[56:57], v[68:69] op_sel_hi:[1,0]
	v_pk_mul_f32 v[54:55], v[54:55], v[68:69] op_sel_hi:[1,0]
	v_pk_mul_f32 v[52:53], v[52:53], v[68:69] op_sel_hi:[1,0]
	v_pk_mul_f32 v[70:71], v[50:51], v[68:69] op_sel_hi:[1,0]
	v_pk_mul_f32 v[68:69], v[48:49], v[68:69] op_sel_hi:[1,0]
	v_cvt_pk_bf16_f32 v48, v60, v61
	v_cvt_pk_bf16_f32 v49, v62, v63
	v_cvt_pk_bf16_f32 v50, v56, v57
	v_cvt_pk_bf16_f32 v51, v58, v59
	global_store_dwordx4 v[66:67], v[48:51], off
	s_nop 7
	s_nop 1
	v_cvt_pk_bf16_f32 v48, v52, v53
	v_cvt_pk_bf16_f32 v49, v54, v55
	v_cvt_pk_bf16_f32 v50, v68, v69
	v_cvt_pk_bf16_f32 v51, v70, v71
	global_store_dwordx4 v[64:65], v[48:51], off offset:256
	s_nop 7
	s_nop 7
	s_nop 0
	v_lshl_add_u64 v[48:49], v[158:159], 0, s[0:1]
	s_mov_b64 s[0:1], 0xa0000
	v_fmamk_f32 v50, v243, 0x3a000000, v198
	v_mul_f32_e32 v51, 0x4b800000, v50
	v_cmp_gt_f32_e32 vcc, s60, v50
	s_nop 1
	v_cndmask_b32_e32 v50, v50, v51, vcc
	v_rsq_f32_e32 v52, v50
	v_add_co_u32_e64 v50, s[6:7], s3, v158
	s_mov_b32 s3, 0xa0000
	v_mul_f32_e32 v53, 0x45800000, v52
	v_cndmask_b32_e32 v52, v52, v53, vcc
	v_mul_f32_e32 v52, 0x3e38aa3b, v52
	v_addc_co_u32_e64 v51, s[6:7], 0, v159, s[6:7]
	v_pk_mul_f32 v[46:47], v[46:47], v[52:53] op_sel_hi:[1,0]
	v_pk_mul_f32 v[44:45], v[44:45], v[52:53] op_sel_hi:[1,0]
	v_pk_mul_f32 v[42:43], v[42:43], v[52:53] op_sel_hi:[1,0]
	v_pk_mul_f32 v[40:41], v[40:41], v[52:53] op_sel_hi:[1,0]
	v_pk_mul_f32 v[38:39], v[38:39], v[52:53] op_sel_hi:[1,0]
	v_pk_mul_f32 v[36:37], v[36:37], v[52:53] op_sel_hi:[1,0]
	v_pk_mul_f32 v[54:55], v[34:35], v[52:53] op_sel_hi:[1,0]
	v_pk_mul_f32 v[52:53], v[32:33], v[52:53] op_sel_hi:[1,0]
	v_cvt_pk_bf16_f32 v32, v44, v45
	v_cvt_pk_bf16_f32 v33, v46, v47
	v_cvt_pk_bf16_f32 v34, v40, v41
	v_cvt_pk_bf16_f32 v35, v42, v43
	global_store_dwordx4 v[50:51], v[32:35], off
	s_nop 7
	s_nop 1
	v_cvt_pk_bf16_f32 v32, v36, v37
	v_cvt_pk_bf16_f32 v33, v38, v39
	v_cvt_pk_bf16_f32 v34, v52, v53
	v_cvt_pk_bf16_f32 v35, v54, v55
	global_store_dwordx4 v[48:49], v[32:35], off offset:256
	s_nop 7
	s_nop 7
	s_nop 0
	v_lshl_add_u64 v[32:33], v[158:159], 0, s[0:1]
	s_mov_b64 s[0:1], 0xb0000
	v_fmamk_f32 v34, v244, 0x3a000000, v198
	v_mul_f32_e32 v35, 0x4b800000, v34
	v_cmp_gt_f32_e32 vcc, s60, v34
	s_nop 1
	v_cndmask_b32_e32 v34, v34, v35, vcc
	v_rsq_f32_e32 v36, v34
	v_add_co_u32_e64 v34, s[6:7], s3, v158
	s_mov_b32 s3, 0xb0000
	v_mul_f32_e32 v37, 0x45800000, v36
	v_cndmask_b32_e32 v36, v36, v37, vcc
	v_mul_f32_e32 v36, 0x3e38aa3b, v36
	v_addc_co_u32_e64 v35, s[6:7], 0, v159, s[6:7]
	v_pk_mul_f32 v[30:31], v[30:31], v[36:37] op_sel_hi:[1,0]
	v_pk_mul_f32 v[28:29], v[28:29], v[36:37] op_sel_hi:[1,0]
	v_pk_mul_f32 v[26:27], v[26:27], v[36:37] op_sel_hi:[1,0]
	v_pk_mul_f32 v[24:25], v[24:25], v[36:37] op_sel_hi:[1,0]
	v_pk_mul_f32 v[22:23], v[22:23], v[36:37] op_sel_hi:[1,0]
	v_pk_mul_f32 v[20:21], v[20:21], v[36:37] op_sel_hi:[1,0]
	v_pk_mul_f32 v[38:39], v[18:19], v[36:37] op_sel_hi:[1,0]
	v_pk_mul_f32 v[36:37], v[16:17], v[36:37] op_sel_hi:[1,0]
	v_cvt_pk_bf16_f32 v16, v28, v29
	v_cvt_pk_bf16_f32 v17, v30, v31
	v_cvt_pk_bf16_f32 v18, v24, v25
	v_cvt_pk_bf16_f32 v19, v26, v27
	global_store_dwordx4 v[34:35], v[16:19], off
	s_nop 7
	s_nop 1
	v_cvt_pk_bf16_f32 v16, v20, v21
	v_cvt_pk_bf16_f32 v17, v22, v23
	v_cvt_pk_bf16_f32 v18, v36, v37
	v_cvt_pk_bf16_f32 v19, v38, v39
	global_store_dwordx4 v[32:33], v[16:19], off offset:256
	s_nop 7
	s_nop 7
	s_nop 0
	v_lshl_add_u64 v[16:17], v[158:159], 0, s[0:1]
	v_fmamk_f32 v18, v245, 0x3a000000, v198
	v_mul_f32_e32 v19, 0x4b800000, v18
	v_cmp_gt_f32_e32 vcc, s60, v18
	s_nop 1
	v_cndmask_b32_e32 v18, v18, v19, vcc
	v_rsq_f32_e32 v20, v18
	v_add_co_u32_e64 v18, s[6:7], s3, v158
	v_mul_f32_e32 v21, 0x45800000, v20
	v_cndmask_b32_e32 v20, v20, v21, vcc
	v_mul_f32_e32 v20, 0x3e38aa3b, v20
	v_addc_co_u32_e64 v19, s[6:7], 0, v159, s[6:7]
	v_pk_mul_f32 v[14:15], v[14:15], v[20:21] op_sel_hi:[1,0]
	v_pk_mul_f32 v[12:13], v[12:13], v[20:21] op_sel_hi:[1,0]
	v_pk_mul_f32 v[10:11], v[10:11], v[20:21] op_sel_hi:[1,0]
	v_pk_mul_f32 v[8:9], v[8:9], v[20:21] op_sel_hi:[1,0]
	v_pk_mul_f32 v[6:7], v[6:7], v[20:21] op_sel_hi:[1,0]
	v_pk_mul_f32 v[4:5], v[4:5], v[20:21] op_sel_hi:[1,0]
	v_pk_mul_f32 v[22:23], v[2:3], v[20:21] op_sel_hi:[1,0]
	v_pk_mul_f32 v[20:21], v[0:1], v[20:21] op_sel_hi:[1,0]
	v_cvt_pk_bf16_f32 v0, v12, v13
	v_cvt_pk_bf16_f32 v1, v14, v15
	v_cvt_pk_bf16_f32 v2, v8, v9
	v_cvt_pk_bf16_f32 v3, v10, v11
	global_store_dwordx4 v[18:19], v[0:3], off
	s_nop 7
	s_nop 1
	v_cvt_pk_bf16_f32 v0, v4, v5
	v_cvt_pk_bf16_f32 v1, v6, v7
	v_cvt_pk_bf16_f32 v2, v20, v21
	v_cvt_pk_bf16_f32 v3, v22, v23
	global_store_dwordx4 v[16:17], v[0:3], off offset:256
	s_nop 7
